# GEMM prologues: second K-tile's LDS-DMA loads issued before the wait+barrier that retire the first K-tile
# baseline (speedup 1.0000x reference)
.LBB0_114:
	s_lshl_b32 s23, s23, 5
	s_mov_b64 s[74:75], 0x80
	s_and_b32 s33, s23, 0x60
	s_add_i32 m0, s17, 0x18000
	v_lshl_add_u64 v[6:7], v[6:7], 0, s[74:75]
	s_lshl_b32 s7, s6, 13
	s_lshl_b32 s52, s33, 7
	global_load_lds_dwordx4 v[6:7], off
	v_lshl_add_u64 v[4:5], v[4:5], 0, s[74:75]
	s_add_i32 m0, s17, 0x1a000
	s_add_i32 s23, s17, 0x8000
	s_add_i32 s24, s17, 0xa000
	global_load_lds_dwordx4 v[4:5], off
	v_lshl_add_u64 v[2:3], v[2:3], 0, s[74:75]
	s_mov_b32 m0, s23
	s_add_u32 s26, s90, 0x40080
	global_load_lds_dwordx4 v[2:3], off
	v_lshl_add_u64 v[0:1], v[0:1], 0, s[74:75]
	s_mov_b32 m0, s24
	s_addc_u32 s27, s91, 0
	global_load_lds_dwordx4 v[0:1], off
	s_add_i32 m0, s17, 0x1c000
	v_lshl_add_u64 v[0:1], s[26:27], 0, v[140:141]
	global_load_lds_dwordx4 v[0:1], off
	v_lshl_add_u64 v[0:1], s[26:27], 0, v[136:137]
	s_add_i32 m0, s17, 0x1e000
	v_mov_b32_e32 v145, 0
	global_load_lds_dwordx4 v[0:1], off
	s_waitcnt vmcnt(8)
	s_barrier
	v_and_b32_e32 v0, 15, v240
	v_bfe_u32 v1, v240, 4, 2
	v_lshl_or_b32 v174, s6, 6, v0
	s_lshl_b32 s6, s6, 8
	v_lshlrev_b32_e32 v144, 4, v1
	s_add_i32 s6, s6, 0
	v_lshl_or_b32 v2, v0, 6, v144
	v_lshlrev_b32_e32 v0, 2, v0
	s_add_i32 s6, s6, 0x20400
	v_and_b32_e32 v3, 32, v0
	v_add_u32_e32 v176, s6, v0
	v_lshlrev_b32_e32 v0, 8, v240
	v_lshl_or_b32 v177, v1, 3, s33
	v_and_b32_e32 v0, 0x38000, v0
	v_lshlrev_b32_e32 v1, 11, v15
	v_bitop3_b32 v2, v2, s7, v3 bitop3:0xde
	v_lshlrev_b32_e32 v3, 6, v240
	s_movk_i32 s7, 0x3c0
	v_or3_b32 v0, v13, v0, v1
	v_and_or_b32 v3, v3, s7, v144
	v_lshlrev_b32_e32 v4, 2, v240
	v_lshl_add_u64 v[146:147], s[70:71], 0, v[144:145]
	v_add_u32_e32 v144, v0, v14
	v_lshlrev_b32_e32 v0, 4, v12
	v_and_b32_e32 v4, 32, v4
	s_waitcnt vmcnt(6)
	s_cmpk_lt_u32 s25, 0x100
	v_and_b32_e32 v0, 0x78000, v0
	s_sext_i32_i8 s54, s76
	v_bitop3_b32 v175, s52, v3, v4 bitop3:0xf6
	s_cselect_b64 s[76:77], -1, 0
	v_or3_b32 v0, v13, v0, v1
	s_add_i32 s25, 0, 0x10000
	s_add_i32 s26, 0, 0x14000
	s_mov_b32 s55, 0
	v_add_u32_e32 v148, v0, v14
	v_mov_b32_e32 v149, v145
	v_mov_b64_e32 v[150:151], 0xb00
	v_mov_b64_e32 v[152:153], 0xaff
	v_add_u32_e32 v178, s25, v175
	v_add_u32_e32 v179, s26, v175
	v_add_u32_e32 v180, 0, v2
	v_mov_b32_e32 v181, 0x358637bd
	s_movk_i32 s27, 0x1600
	s_barrier
	s_branch .LBB0_117

.LBB0_258:
	v_bfe_u32 v12, v240, 4, 2
	v_and_b32_e32 v13, 15, v240
	v_lshlrev_b32_e32 v15, 4, v12
	v_lshlrev_b32_e32 v16, 2, v240
	s_and_b32 s20, s6, 3
	v_lshl_or_b32 v242, s7, 6, v13
	v_lshl_or_b32 v13, v13, 6, v15
	s_lshl_b32 s6, s7, 13
	v_and_b32_e32 v16, 32, v16
	s_mov_b64 s[80:81], 0x80
	v_bitop3_b32 v13, v13, s6, v16 bitop3:0xde
	v_lshlrev_b32_e32 v17, 6, v240
	s_movk_i32 s6, 0x3c0
	s_add_i32 m0, s16, 0x18000
	v_lshl_add_u64 v[6:7], v[6:7], 0, s[80:81]
	v_and_or_b32 v15, v17, s6, v15
	s_lshl_b32 s6, s20, 12
	global_load_lds_dwordx4 v[6:7], off
	v_lshl_add_u64 v[4:5], v[4:5], 0, s[80:81]
	s_add_i32 m0, s16, 0x1a000
	s_add_i32 s21, s16, 0x8000
	s_add_i32 s22, s16, 0xa000
	v_bitop3_b32 v243, s6, v15, v16 bitop3:0xf6
	global_load_lds_dwordx4 v[4:5], off
	v_lshl_add_u64 v[0:1], v[0:1], 0, s[80:81]
	s_mov_b32 m0, s21
	s_add_u32 s6, s88, 0xb0080
	global_load_lds_dwordx4 v[0:1], off
	v_lshl_add_u64 v[0:1], v[2:3], 0, s[80:81]
	s_mov_b32 m0, s22
	s_addc_u32 s7, s89, 0
	global_load_lds_dwordx4 v[0:1], off
	s_add_i32 m0, s16, 0x1c000
	v_lshl_add_u64 v[0:1], s[6:7], 0, v[194:195]
	global_load_lds_dwordx4 v[0:1], off
	v_lshl_add_u64 v[0:1], s[6:7], 0, v[198:199]
	s_add_i32 m0, s16, 0x1e000
	s_cmpk_lt_u32 s10, 0x100
	global_load_lds_dwordx4 v[0:1], off
	s_waitcnt vmcnt(8)
	s_barrier
	v_add_u16_e32 v0, v8, v9
	s_waitcnt vmcnt(6)
	v_lshrrev_b16_e32 v0, 1, v0
	s_waitcnt lgkmcnt(0)
	v_lshlrev_b32_e32 v14, 3, v12
	s_cselect_b64 s[82:83], -1, 0
	v_add_lshl_u32 v200, v10, v0, 1
	v_add_lshl_u32 v202, v11, v0, 1
	s_add_i32 s26, 0, 0x10000
	s_add_i32 s27, 0, 0x14000
	v_mbcnt_lo_u32_b32 v0, -1, 0
	v_lshl_or_b32 v244, s20, 5, v14
	v_cmp_eq_u32_e64 s[6:7], 0, v12
	s_ashr_i32 s23, s34, 31
	s_mov_b32 s24, s34
	s_ashr_i32 s25, s2, 31
	v_mov_b32_e32 v201, v195
	v_mov_b32_e32 v203, v195
	v_add_u32_e32 v245, s26, v243
	v_add_u32_e32 v246, s27, v243
	v_add_u32_e32 v247, 0, v13
	v_mbcnt_hi_u32_b32 v248, -1, v0
	s_mov_b32 s33, 0
	s_barrier
	s_branch .LBB0_261

.LBB0_423:
	s_mov_b64 s[80:81], 0x80
	s_lshl_b32 s9, s8, 8
	s_and_b32 s29, s16, 3
	s_add_i32 m0, s58, 0x18000
	v_lshl_add_u64 v[6:7], v[6:7], 0, s[80:81]
	s_add_i32 s10, s9, 0
	s_lshl_b32 s73, s8, 6
	s_lshl_b32 s11, s8, 13
	s_lshl_b32 s17, s29, 12
	global_load_lds_dwordx4 v[6:7], off
	v_lshl_add_u64 v[4:5], v[4:5], 0, s[80:81]
	s_add_i32 m0, s58, 0x1a000
	s_add_i32 s93, s58, 0x8000
	s_add_i32 s69, s58, 0xa000
	global_load_lds_dwordx4 v[4:5], off
	v_lshl_add_u64 v[2:3], v[2:3], 0, s[80:81]
	s_mov_b32 m0, s93
	s_add_u32 s8, s6, 0x40080
	global_load_lds_dwordx4 v[2:3], off
	v_lshl_add_u64 v[0:1], v[0:1], 0, s[80:81]
	s_mov_b32 m0, s69
	s_addc_u32 s9, s7, 0
	global_load_lds_dwordx4 v[0:1], off
	s_add_i32 m0, s58, 0x1c000
	v_lshl_add_u64 v[0:1], s[8:9], 0, v[142:143]
	global_load_lds_dwordx4 v[0:1], off
	v_lshl_add_u64 v[0:1], s[8:9], 0, v[146:147]
	s_add_i32 m0, s58, 0x1e000
	s_movk_i32 s8, 0x3c0
	global_load_lds_dwordx4 v[0:1], off
	s_waitcnt vmcnt(8)
	s_barrier
	v_lshrrev_b32_e32 v0, 4, v240
	v_bfe_u32 v1, v240, 4, 2
	v_lshlrev_b32_e32 v148, 3, v1
	v_lshlrev_b32_e32 v150, 4, v1
	v_lshlrev_b32_e32 v1, 6, v240
	v_lshlrev_b32_e32 v2, 2, v240
	v_bitop3_b32 v0, s16, v0, 3 bitop3:0xa8
	v_and_or_b32 v1, v1, s8, v150
	v_and_b32_e32 v2, 32, v2
	v_cmp_eq_u32_e64 s[8:9], 0, v0
	v_lshlrev_b32_e32 v0, 8, v240
	v_bitop3_b32 v200, s17, v1, v2 bitop3:0xf6
	v_and_b32_e32 v0, 0x38000, v0
	v_lshlrev_b32_e32 v1, 11, v14
	v_and_b32_e32 v199, 15, v240
	v_or3_b32 v0, v12, v0, v1
	v_lshlrev_b32_e32 v3, 2, v199
	s_add_i32 s10, s10, 0x20400
	v_add_u32_e32 v156, v0, v13
	v_lshlrev_b32_e32 v0, 4, v15
	v_lshl_or_b32 v4, v199, 6, v150
	v_and_b32_e32 v5, 32, v3
	s_waitcnt vmcnt(6)
	s_cmpk_lt_u32 s15, 0x100
	v_and_b32_e32 v0, 0x78000, v0
	v_mov_b32_e32 v151, 0
	v_bitop3_b32 v4, v4, s11, v5 bitop3:0xde
	v_lshl_or_b32 v154, s29, 5, v148
	s_cselect_b64 s[82:83], -1, 0
	v_or3_b32 v0, v12, v0, v1
	s_add_i32 s76, 0, 0x10000
	s_add_i32 s77, 0, 0x14000
	s_mov_b32 s14, 0
	v_lshl_add_u64 v[152:153], s[70:71], 0, v[150:151]
	v_add_u32_e32 v201, s10, v3
	v_or_b32_e32 v202, 0xfffff800, v154
	v_writelane_b32 v254, s8, 57
	v_mov_b32_e32 v157, v151
	v_add_u32_e32 v158, v0, v13
	v_mov_b32_e32 v159, v151
	v_mov_b64_e32 v[160:161], 0x500
	v_mov_b64_e32 v[162:163], 0x4ff
	v_add_u32_e32 v203, s76, v200
	v_add_u32_e32 v204, s77, v200
	v_add_u32_e32 v205, 0, v4
	v_mov_b32_e32 v206, 0x358637bd
	s_mov_b32 s87, 0xbfb8aa3b
	s_mov_b32 s10, 0x3f2aaaab
	v_mov_b32_e32 v207, 0x3ecc95a3
	s_mov_b32 s11, 0x3f317218
	s_mov_b32 s33, 0x7f800000
	s_mov_b32 s78, 0x33800000
	s_mov_b32 s36, 0x40000
	s_mov_b32 s37, 0x48000
	s_mov_b32 s38, 0x50000
	v_mov_b32_e32 v208, 0x7f800000
	v_mov_b32_e32 v209, 0x7fc00000
	v_mov_b32_e32 v210, 0xff800000
	v_mov_b32_e32 v211, 0x3e38aa3b
	s_barrier
	v_writelane_b32 v254, s9, 58
	s_branch .LBB0_426

.LBB0_983:
	s_mov_b64 s[46:47], 0x80
	s_and_b32 s20, s5, 3
	s_add_i32 m0, s16, 0x18000
	v_lshl_add_u64 v[6:7], v[6:7], 0, s[46:47]
	s_lshl_b32 s5, s4, 13
	s_lshl_b32 s24, s20, 12
	global_load_lds_dwordx4 v[6:7], off
	v_lshl_add_u64 v[4:5], v[4:5], 0, s[46:47]
	s_add_i32 m0, s16, 0x1a000
	s_add_i32 s21, s16, 0x8000
	s_add_i32 s22, s16, 0xa000
	global_load_lds_dwordx4 v[4:5], off
	v_lshl_add_u64 v[0:1], v[0:1], 0, s[46:47]
	s_mov_b32 m0, s21
	s_add_u32 s6, s84, 0x40080
	global_load_lds_dwordx4 v[0:1], off
	v_lshl_add_u64 v[0:1], v[2:3], 0, s[46:47]
	s_mov_b32 m0, s22
	s_addc_u32 s7, s85, 0
	global_load_lds_dwordx4 v[0:1], off
	s_add_i32 m0, s16, 0x1c000
	v_lshl_add_u64 v[0:1], s[6:7], 0, v[194:195]
	global_load_lds_dwordx4 v[0:1], off
	v_lshl_add_u64 v[0:1], s[6:7], 0, v[198:199]
	s_add_i32 m0, s16, 0x1e000
	v_lshlrev_b32_e32 v4, 2, v240
	global_load_lds_dwordx4 v[0:1], off
	s_waitcnt vmcnt(8)
	s_barrier
	v_bfe_u32 v0, v240, 4, 2
	v_and_b32_e32 v1, 15, v240
	v_lshlrev_b32_e32 v3, 4, v0
	v_lshl_or_b32 v242, s4, 6, v1
	v_lshl_or_b32 v1, v1, 6, v3
	v_and_b32_e32 v4, 32, v4
	v_lshlrev_b32_e32 v5, 6, v240
	s_movk_i32 s4, 0x3c0
	v_lshlrev_b32_e32 v2, 3, v0
	v_bitop3_b32 v1, v1, s5, v4 bitop3:0xde
	v_and_or_b32 v3, v5, s4, v3
	v_cmp_eq_u32_e64 s[4:5], 0, v0
	v_lshlrev_b32_e32 v0, 8, v240
	v_lshl_or_b32 v244, s20, 5, v2
	v_and_b32_e32 v0, 0x38000, v0
	v_lshlrev_b32_e32 v2, 11, v10
	v_or3_b32 v0, v8, v0, v2
	v_add_u32_e32 v200, v0, v9
	v_lshlrev_b32_e32 v0, 4, v11
	v_and_b32_e32 v0, 0x78000, v0
	s_waitcnt vmcnt(6)
	s_cmpk_lt_u32 s23, 0x100
	v_or3_b32 v0, v8, v0, v2
	v_bitop3_b32 v243, s24, v3, v4 bitop3:0xf6
	s_cselect_b64 s[48:49], -1, 0
	v_add_u32_e32 v202, v0, v9
	s_add_i32 s26, 0, 0x10000
	s_add_i32 s27, 0, 0x14000
	v_mbcnt_lo_u32_b32 v0, -1, 0
	s_ashr_i32 s23, s34, 31
	s_mov_b32 s24, s34
	s_ashr_i32 s25, s2, 31
	v_mov_b32_e32 v201, v195
	v_mov_b32_e32 v203, v195
	v_add_u32_e32 v245, s26, v243
	v_add_u32_e32 v246, s27, v243
	v_add_u32_e32 v247, 0, v1
	v_mbcnt_hi_u32_b32 v248, -1, v0
	s_mov_b32 s33, 0
	s_barrier
	s_branch .LBB0_986

.LBB0_1142:
	s_lshl_b32 s10, s23, 5
	s_and_b32 s33, s10, 0x60
	s_mov_b64 s[10:11], 0x80
	s_add_i32 m0, s17, 0x18000
	v_lshl_add_u64 v[6:7], v[6:7], 0, s[10:11]
	s_lshl_b32 s5, s4, 13
	s_lshl_b32 s45, s33, 7
	global_load_lds_dwordx4 v[6:7], off
	v_lshl_add_u64 v[4:5], v[4:5], 0, s[10:11]
	s_add_i32 m0, s17, 0x1a000
	s_add_i32 s23, s17, 0x8000
	s_add_i32 s24, s17, 0xa000
	global_load_lds_dwordx4 v[4:5], off
	v_lshl_add_u64 v[2:3], v[2:3], 0, s[10:11]
	s_mov_b32 m0, s23
	s_add_u32 s26, s80, 0x40080
	global_load_lds_dwordx4 v[2:3], off
	v_lshl_add_u64 v[0:1], v[0:1], 0, s[10:11]
	s_mov_b32 m0, s24
	s_addc_u32 s27, s81, 0
	global_load_lds_dwordx4 v[0:1], off
	s_add_i32 m0, s17, 0x1c000
	v_lshl_add_u64 v[0:1], s[26:27], 0, v[132:133]
	global_load_lds_dwordx4 v[0:1], off
	v_lshl_add_u64 v[0:1], s[26:27], 0, v[128:129]
	s_add_i32 m0, s17, 0x1e000
	v_mov_b32_e32 v137, 0
	global_load_lds_dwordx4 v[0:1], off
	s_waitcnt vmcnt(8)
	s_barrier
	v_and_b32_e32 v0, 15, v240
	v_bfe_u32 v1, v240, 4, 2
	v_lshl_or_b32 v170, s4, 6, v0
	s_lshl_b32 s4, s4, 8
	v_lshlrev_b32_e32 v136, 4, v1
	s_add_i32 s4, s4, 0
	v_lshl_or_b32 v2, v0, 6, v136
	v_lshlrev_b32_e32 v0, 2, v0
	s_add_i32 s4, s4, 0x20400
	v_and_b32_e32 v3, 32, v0
	v_add_u32_e32 v172, s4, v0
	v_lshlrev_b32_e32 v0, 8, v240
	v_lshl_or_b32 v173, v1, 3, s33
	v_and_b32_e32 v0, 0x38000, v0
	v_lshlrev_b32_e32 v1, 11, v15
	v_bitop3_b32 v2, v2, s5, v3 bitop3:0xde
	v_lshlrev_b32_e32 v3, 6, v240
	s_movk_i32 s5, 0x3c0
	v_or3_b32 v0, v13, v0, v1
	v_and_or_b32 v3, v3, s5, v136
	v_lshlrev_b32_e32 v4, 2, v240
	v_lshl_add_u64 v[138:139], s[70:71], 0, v[136:137]
	v_add_u32_e32 v136, v0, v14
	v_lshlrev_b32_e32 v0, 4, v12
	v_and_b32_e32 v4, 32, v4
	s_waitcnt vmcnt(6)
	s_cmpk_lt_u32 s25, 0x100
	v_and_b32_e32 v0, 0x78000, v0
	s_sext_i32_i8 s56, s44
	v_bitop3_b32 v171, s45, v3, v4 bitop3:0xf6
	s_cselect_b64 s[44:45], -1, 0
	v_or3_b32 v0, v13, v0, v1
	s_add_i32 s25, 0, 0x10000
	s_add_i32 s26, 0, 0x14000
	s_mov_b32 s57, 0
	v_add_u32_e32 v140, v0, v14
	v_mov_b32_e32 v141, v137
	v_mov_b64_e32 v[142:143], 0xb00
	v_mov_b64_e32 v[144:145], 0xaff
	v_add_u32_e32 v174, s25, v171
	v_add_u32_e32 v175, s26, v171
	v_add_u32_e32 v176, 0, v2
	v_mov_b32_e32 v177, 0x358637bd
	s_movk_i32 s27, 0x1600
	s_barrier
	s_branch .LBB0_1145

.LBB0_1285:
	s_mov_b64 s[48:49], 0x80
	s_and_b32 s20, s5, 3
	s_add_i32 m0, s16, 0x18000
	v_lshl_add_u64 v[6:7], v[6:7], 0, s[48:49]
	s_lshl_b32 s5, s4, 13
	s_lshl_b32 s9, s20, 12
	global_load_lds_dwordx4 v[6:7], off
	v_lshl_add_u64 v[4:5], v[4:5], 0, s[48:49]
	s_add_i32 m0, s16, 0x1a000
	s_add_i32 s21, s16, 0x8000
	s_add_i32 s22, s16, 0xa000
	global_load_lds_dwordx4 v[4:5], off
	v_lshl_add_u64 v[0:1], v[0:1], 0, s[48:49]
	s_mov_b32 m0, s21
	s_add_u32 s6, s78, 0xb0080
	global_load_lds_dwordx4 v[0:1], off
	v_lshl_add_u64 v[0:1], v[2:3], 0, s[48:49]
	s_mov_b32 m0, s22
	s_addc_u32 s7, s79, 0
	global_load_lds_dwordx4 v[0:1], off
	s_add_i32 m0, s16, 0x1c000
	v_lshl_add_u64 v[0:1], s[6:7], 0, v[194:195]
	global_load_lds_dwordx4 v[0:1], off
	v_lshl_add_u64 v[0:1], s[6:7], 0, v[198:199]
	s_add_i32 m0, s16, 0x1e000
	v_lshlrev_b32_e32 v4, 2, v240
	global_load_lds_dwordx4 v[0:1], off
	s_waitcnt vmcnt(8)
	s_barrier
	v_bfe_u32 v0, v240, 4, 2
	v_and_b32_e32 v1, 15, v240
	v_lshlrev_b32_e32 v3, 4, v0
	v_lshl_or_b32 v242, s4, 6, v1
	v_lshl_or_b32 v1, v1, 6, v3
	v_and_b32_e32 v4, 32, v4
	v_lshlrev_b32_e32 v5, 6, v240
	s_movk_i32 s4, 0x3c0
	v_lshlrev_b32_e32 v2, 3, v0
	v_bitop3_b32 v1, v1, s5, v4 bitop3:0xde
	v_and_or_b32 v3, v5, s4, v3
	v_cmp_eq_u32_e64 s[4:5], 0, v0
	v_add_u16_e32 v0, v8, v9
	s_waitcnt vmcnt(6)
	s_cmpk_lt_u32 s8, 0x100
	v_lshrrev_b16_e32 v0, 1, v0
	v_bitop3_b32 v243, s9, v3, v4 bitop3:0xf6
	s_cselect_b64 s[50:51], -1, 0
	v_add_lshl_u32 v200, v10, v0, 1
	v_add_lshl_u32 v202, v11, v0, 1
	s_add_i32 s26, 0, 0x10000
	s_add_i32 s27, 0, 0x14000
	v_mbcnt_lo_u32_b32 v0, -1, 0
	v_lshl_or_b32 v244, s20, 5, v2
	s_ashr_i32 s23, s34, 31
	s_mov_b32 s24, s34
	s_ashr_i32 s25, s2, 31
	v_mov_b32_e32 v201, v195
	v_mov_b32_e32 v203, v195
	v_add_u32_e32 v245, s26, v243
	v_add_u32_e32 v246, s27, v243
	v_add_u32_e32 v247, 0, v1
	v_mbcnt_hi_u32_b32 v248, -1, v0
	s_mov_b32 s33, 0
	s_barrier
	s_branch .LBB0_1288

.LBB0_1754:
	s_lshl_b32 s10, s23, 5
	s_and_b32 s45, s10, 0x60
	s_mov_b64 s[10:11], 0x80
	s_lshl_b32 s5, s4, 8
	s_add_i32 m0, s18, 0x18000
	v_lshl_add_u64 v[6:7], v[6:7], 0, s[10:11]
	s_add_i32 s5, s5, 0
	s_lshl_b32 s33, s4, 13
	s_lshl_b32 s46, s45, 7
	global_load_lds_dwordx4 v[6:7], off
	v_lshl_add_u64 v[4:5], v[4:5], 0, s[10:11]
	s_add_i32 m0, s18, 0x1a000
	s_add_i32 s23, s18, 0x8000
	s_add_i32 s24, s18, 0xa000
	global_load_lds_dwordx4 v[4:5], off
	v_lshl_add_u64 v[2:3], v[2:3], 0, s[10:11]
	s_mov_b32 m0, s23
	s_add_u32 s26, s80, 0x40080
	global_load_lds_dwordx4 v[2:3], off
	v_lshl_add_u64 v[0:1], v[0:1], 0, s[10:11]
	s_mov_b32 m0, s24
	s_addc_u32 s27, s81, 0
	global_load_lds_dwordx4 v[0:1], off
	s_add_i32 m0, s18, 0x1c000
	v_lshl_add_u64 v[0:1], s[26:27], 0, v[142:143]
	global_load_lds_dwordx4 v[0:1], off
	v_lshl_add_u64 v[0:1], s[26:27], 0, v[146:147]
	s_add_i32 m0, s18, 0x1e000
	v_lshlrev_b32_e32 v2, 6, v240
	global_load_lds_dwordx4 v[0:1], off
	s_waitcnt vmcnt(8)
	s_barrier
	v_bfe_u32 v1, v240, 4, 2
	v_lshlrev_b32_e32 v148, 4, v1
	s_movk_i32 s26, 0x3c0
	v_lshlrev_b32_e32 v3, 2, v240
	v_and_or_b32 v2, v2, s26, v148
	v_and_b32_e32 v3, 32, v3
	v_lshl_or_b32 v179, v1, 3, s45
	v_lshlrev_b32_e32 v1, 8, v240
	v_bitop3_b32 v177, s46, v2, v3 bitop3:0xf6
	v_and_b32_e32 v1, 0x38000, v1
	v_lshlrev_b32_e32 v2, 11, v14
	v_and_b32_e32 v0, 15, v240
	v_or3_b32 v1, v12, v1, v2
	v_lshlrev_b32_e32 v4, 2, v0
	s_add_i32 s5, s5, 0x20400
	v_add_u32_e32 v152, v1, v13
	v_lshlrev_b32_e32 v1, 4, v15
	v_lshl_or_b32 v176, s4, 6, v0
	v_lshl_or_b32 v0, v0, 6, v148
	v_and_b32_e32 v5, 32, v4
	s_waitcnt vmcnt(6)
	s_cmpk_lt_u32 s25, 0x100
	v_and_b32_e32 v1, 0x78000, v1
	s_sext_i32_i8 s58, s44
	v_mov_b32_e32 v149, 0
	v_bitop3_b32 v0, v0, s33, v5 bitop3:0xde
	s_cselect_b64 s[44:45], -1, 0
	v_or3_b32 v1, v12, v1, v2
	s_add_i32 s25, 0, 0x10000
	s_add_i32 s26, 0, 0x14000
	s_mov_b32 s59, 0
	v_lshl_add_u64 v[150:151], s[70:71], 0, v[148:149]
	v_add_u32_e32 v178, s5, v4
	v_or_b32_e32 v180, 0xfffff800, v179
	v_mov_b32_e32 v153, v149
	v_add_u32_e32 v154, v1, v13
	v_mov_b32_e32 v155, v149
	v_mov_b64_e32 v[156:157], 0x600
	v_mov_b64_e32 v[158:159], 0x5ff
	v_add_u32_e32 v181, s25, v177
	v_add_u32_e32 v182, s26, v177
	v_add_u32_e32 v183, 0, v0
	v_mov_b32_e32 v184, 0x358637bd
	s_mov_b32 s27, 0x40000
	s_mov_b32 s33, 0x48000
	s_mov_b32 s56, 0x50000
	s_barrier
	s_branch .LBB0_1757

.LBB0_2027:
	s_mov_b64 s[46:47], 0x80
	s_and_b32 s20, s5, 3
	s_add_i32 m0, s16, 0x18000
	v_lshl_add_u64 v[6:7], v[6:7], 0, s[46:47]
	s_lshl_b32 s5, s4, 13
	s_lshl_b32 s24, s20, 12
	global_load_lds_dwordx4 v[6:7], off
	v_lshl_add_u64 v[4:5], v[4:5], 0, s[46:47]
	s_add_i32 m0, s16, 0x1a000
	s_add_i32 s21, s16, 0x8000
	s_add_i32 s22, s16, 0xa000
	global_load_lds_dwordx4 v[4:5], off
	v_lshl_add_u64 v[0:1], v[0:1], 0, s[46:47]
	s_mov_b32 m0, s21
	s_add_u32 s6, s78, 0x40080
	global_load_lds_dwordx4 v[0:1], off
	v_lshl_add_u64 v[0:1], v[2:3], 0, s[46:47]
	s_mov_b32 m0, s22
	s_addc_u32 s7, s79, 0
	global_load_lds_dwordx4 v[0:1], off
	s_add_i32 m0, s16, 0x1c000
	v_lshl_add_u64 v[0:1], s[6:7], 0, v[194:195]
	global_load_lds_dwordx4 v[0:1], off
	v_lshl_add_u64 v[0:1], s[6:7], 0, v[198:199]
	s_add_i32 m0, s16, 0x1e000
	v_lshlrev_b32_e32 v4, 2, v240
	global_load_lds_dwordx4 v[0:1], off
	s_waitcnt vmcnt(8)
	s_barrier
	v_bfe_u32 v0, v240, 4, 2
	v_and_b32_e32 v1, 15, v240
	v_lshlrev_b32_e32 v3, 4, v0
	v_lshl_or_b32 v242, s4, 6, v1
	v_lshl_or_b32 v1, v1, 6, v3
	v_and_b32_e32 v4, 32, v4
	v_lshlrev_b32_e32 v5, 6, v240
	s_movk_i32 s4, 0x3c0
	v_lshlrev_b32_e32 v2, 3, v0
	v_bitop3_b32 v1, v1, s5, v4 bitop3:0xde
	v_and_or_b32 v3, v5, s4, v3
	v_cmp_eq_u32_e64 s[4:5], 0, v0
	v_lshlrev_b32_e32 v0, 8, v240
	v_lshl_or_b32 v244, s20, 5, v2
	v_and_b32_e32 v0, 0x38000, v0
	v_lshlrev_b32_e32 v2, 11, v10
	v_or3_b32 v0, v8, v0, v2
	v_add_u32_e32 v200, v0, v9
	v_lshlrev_b32_e32 v0, 4, v11
	v_and_b32_e32 v0, 0x78000, v0
	s_waitcnt vmcnt(6)
	s_cmpk_lt_u32 s23, 0x100
	v_or3_b32 v0, v8, v0, v2
	v_bitop3_b32 v243, s24, v3, v4 bitop3:0xf6
	s_cselect_b64 s[48:49], -1, 0
	v_add_u32_e32 v202, v0, v9
	s_add_i32 s26, 0, 0x10000
	s_add_i32 s27, 0, 0x14000
	v_mbcnt_lo_u32_b32 v0, -1, 0
	s_ashr_i32 s23, s34, 31
	s_mov_b32 s24, s34
	s_ashr_i32 s25, s2, 31
	v_mov_b32_e32 v201, v195
	v_mov_b32_e32 v203, v195
	v_add_u32_e32 v245, s26, v243
	v_add_u32_e32 v246, s27, v243
	v_add_u32_e32 v247, 0, v1
	v_mbcnt_hi_u32_b32 v248, -1, v0
	s_mov_b32 s33, 0
	s_barrier
	s_branch .LBB0_2030

.LBB0_2186:
	s_lshl_b32 s10, s23, 5
	s_and_b32 s33, s10, 0x60
	s_mov_b64 s[10:11], 0x80
	s_add_i32 m0, s17, 0x18000
	v_lshl_add_u64 v[6:7], v[6:7], 0, s[10:11]
	s_lshl_b32 s5, s4, 13
	s_lshl_b32 s43, s33, 7
	global_load_lds_dwordx4 v[6:7], off
	v_lshl_add_u64 v[4:5], v[4:5], 0, s[10:11]
	s_add_i32 m0, s17, 0x1a000
	s_add_i32 s23, s17, 0x8000
	s_add_i32 s24, s17, 0xa000
	global_load_lds_dwordx4 v[4:5], off
	v_lshl_add_u64 v[2:3], v[2:3], 0, s[10:11]
	s_mov_b32 m0, s23
	s_add_u32 s26, s72, 0x40080
	global_load_lds_dwordx4 v[2:3], off
	v_lshl_add_u64 v[0:1], v[0:1], 0, s[10:11]
	s_mov_b32 m0, s24
	s_addc_u32 s27, s73, 0
	global_load_lds_dwordx4 v[0:1], off
	s_add_i32 m0, s17, 0x1c000
	v_lshl_add_u64 v[0:1], s[26:27], 0, v[132:133]
	global_load_lds_dwordx4 v[0:1], off
	v_lshl_add_u64 v[0:1], s[26:27], 0, v[128:129]
	s_add_i32 m0, s17, 0x1e000
	v_mov_b32_e32 v137, 0
	global_load_lds_dwordx4 v[0:1], off
	s_waitcnt vmcnt(8)
	s_barrier
	v_and_b32_e32 v0, 15, v240
	v_bfe_u32 v1, v240, 4, 2
	v_lshl_or_b32 v170, s4, 6, v0
	s_lshl_b32 s4, s4, 8
	v_lshlrev_b32_e32 v136, 4, v1
	s_add_i32 s4, s4, 0
	v_lshl_or_b32 v2, v0, 6, v136
	v_lshlrev_b32_e32 v0, 2, v0
	s_add_i32 s4, s4, 0x20400
	v_and_b32_e32 v3, 32, v0
	v_add_u32_e32 v172, s4, v0
	v_lshlrev_b32_e32 v0, 8, v240
	v_lshl_or_b32 v173, v1, 3, s33
	v_and_b32_e32 v0, 0x38000, v0
	v_lshlrev_b32_e32 v1, 11, v15
	v_bitop3_b32 v2, v2, s5, v3 bitop3:0xde
	v_lshlrev_b32_e32 v3, 6, v240
	s_movk_i32 s5, 0x3c0
	v_or3_b32 v0, v13, v0, v1
	v_and_or_b32 v3, v3, s5, v136
	v_lshlrev_b32_e32 v4, 2, v240
	v_lshl_add_u64 v[138:139], s[70:71], 0, v[136:137]
	v_add_u32_e32 v136, v0, v14
	v_lshlrev_b32_e32 v0, 4, v12
	v_and_b32_e32 v4, 32, v4
	s_waitcnt vmcnt(6)
	s_cmpk_lt_u32 s25, 0x100
	v_and_b32_e32 v0, 0x78000, v0
	s_sext_i32_i8 s56, s42
	v_bitop3_b32 v171, s43, v3, v4 bitop3:0xf6
	s_cselect_b64 s[42:43], -1, 0
	v_or3_b32 v0, v13, v0, v1
	s_add_i32 s26, 0, 0x10000
	s_add_i32 s27, 0, 0x14000
	s_mov_b32 s57, 0
	v_add_u32_e32 v140, v0, v14
	v_mov_b32_e32 v141, v137
	v_mov_b64_e32 v[142:143], 0xb00
	v_mov_b64_e32 v[144:145], 0xaff
	s_movk_i32 s25, 0x161
	v_add_u32_e32 v174, s26, v171
	v_add_u32_e32 v175, s27, v171
	v_add_u32_e32 v176, 0, v2
	s_movk_i32 s33, 0x2000
	v_mov_b32_e32 v177, 0x358637bd
	s_movk_i32 s54, 0x1600
	s_barrier
	s_branch .LBB0_2189

.LBB0_2327:
	s_lshl_b32 s5, s5, 5
	s_mov_b64 s[8:9], 0x80
	s_and_b32 s5, s5, 0x60
	s_add_i32 m0, s25, 0x18000
	v_lshl_add_u64 v[6:7], v[6:7], 0, s[8:9]
	s_lshl_b32 s14, s0, 13
	s_lshl_b32 s15, s5, 7
	global_load_lds_dwordx4 v[6:7], off
	v_lshl_add_u64 v[4:5], v[4:5], 0, s[8:9]
	s_add_i32 m0, s25, 0x1a000
	s_add_i32 s33, s25, 0x8000
	s_add_i32 s35, s25, 0xa000
	global_load_lds_dwordx4 v[4:5], off
	v_lshl_add_u64 v[0:1], v[0:1], 0, s[8:9]
	s_mov_b32 m0, s33
	s_add_u32 s10, s18, 0xb0080
	global_load_lds_dwordx4 v[0:1], off
	v_lshl_add_u64 v[0:1], v[2:3], 0, s[8:9]
	s_mov_b32 m0, s35
	s_addc_u32 s11, s19, 0
	global_load_lds_dwordx4 v[0:1], off
	s_add_i32 m0, s25, 0x1c000
	v_lshl_add_u64 v[0:1], s[10:11], 0, v[166:167]
	global_load_lds_dwordx4 v[0:1], off
	v_lshl_add_u64 v[0:1], s[10:11], 0, v[170:171]
	s_add_i32 m0, s25, 0x1e000
	v_lshlrev_b32_e32 v2, 2, v240
	global_load_lds_dwordx4 v[0:1], off
	s_waitcnt vmcnt(8)
	s_barrier
	v_and_b32_e32 v0, 15, v240
	v_lshl_or_b32 v194, s0, 6, v0
	v_lshlrev_b32_e32 v1, 1, v10
	v_lshlrev_b32_e32 v3, 6, v240
	s_movk_i32 s0, 0x3c0
	v_lshl_or_b32 v0, v0, 6, v1
	v_and_b32_e32 v2, 32, v2
	v_and_or_b32 v1, v3, s0, v1
	v_bitop3_b32 v195, s15, v1, v2 bitop3:0xf6
	s_waitcnt vmcnt(6)
	s_cmpk_lt_u32 s4, 0x100
	v_add_u16_e32 v1, v8, v9
	v_bitop3_b32 v0, v0, s14, v2 bitop3:0xde
	s_cselect_b64 s[10:11], -1, 0
	v_lshrrev_b16_e32 v1, 1, v1
	s_add_i32 s37, 0, 0x10000
	s_add_i32 s38, 0, 0x14000
	s_sext_i32_i8 s42, s1
	s_ashr_i32 s36, s34, 31
	v_or_b32_e32 v196, s5, v10
	v_add_lshl_u32 v172, v11, v1, 1
	v_mov_b32_e32 v173, v167
	v_add_lshl_u32 v174, v12, v1, 1
	v_mov_b32_e32 v175, v167
	v_mov_b64_e32 v[176:177], 0x200
	v_mov_b64_e32 v[178:179], 0x1ff
	v_add_u32_e32 v197, s37, v195
	v_add_u32_e32 v198, s38, v195
	v_add_u32_e32 v199, 0, v0
	s_barrier
	s_branch .LBB0_2330
